# P1 GEMM k-loop via 3-stage LDS-DMA (global_load_lds) + cvt_pk_bf16 in GDN chain
# speedup vs baseline: 1.0212x; 1.0034x over previous
;     ...
;   const int ldrow = tid >> 2, ldp = tid & 3;
;   const int lsw = ((ldp ^ ((ldrow >> 2) & 3)) * 16);
;   const int rsw = ((quad ^ ((l15 >> 2) & 3)) * 16);
;     ...
;     const u16* Ag = A + (size_t)(m0 + ldrow) * K + ldp * 8 + kt0 * 32;
;     const u16* Bg = Bt + (size_t)(n0 + ldrow) * K + ldp * 8 + kt0 * 32;
; #pragma unroll
;     for (int i = 0; i < 4; ++i) ra[i] = *(const u32x4*)(Ag + (size_t)(i * 64) * K);
; #pragma unroll
;     for (int i = 0; i < 2; ++i) rb[i] = *(const u32x4*)(Bg + (size_t)(i * 64) * K);
;     __syncthreads();
; #pragma unroll
;     for (int i = 0; i < 4; ++i) *(u32x4*)(smem + (ldrow + i * 64) * 64 + lsw) = ra[i];
; #pragma unroll
;     for (int i = 0; i < 2; ++i) *(u32x4*)(smem + 16384 + (ldrow + i * 64) * 64 + lsw) = rb[i];
.LBB0_117:
	s_or_b64 exec, exec, s[2:3]
	v_readlane_b32 s3, v254, 6
	v_mov_b32_e32 v6, v1
	s_and_b32 s2, s18, 7
	s_ashr_i32 s3, s3, 3
	s_barrier
	s_mul_i32 s2, s3, s2
	v_lshrrev_b32_e32 v4, 4, v6
	v_lshrrev_b32_e32 v9, 2, v6
	s_ashr_i32 s3, s18, 3
	v_xor_b32_e32 v4, v4, v9
	s_add_i32 s2, s2, s3
	v_lshlrev_b32_e32 v5, 4, v6
	v_lshlrev_b32_e32 v4, 4, v4
	v_writelane_b32 v254, s2, 13
	v_readlane_b32 s2, v251, 56
	v_bitop3_b32 v8, v5, 48, v6 bitop3:0x48
	v_and_b32_e32 v10, 48, v4
	v_and_b32_e32 v4, 48, v5
	v_mov_b32_e32 v5, v2
	v_readlane_b32 s3, v251, 57
	v_bfe_u32 v7, v6, 6, 1
	v_ashrrev_i32_e32 v3, 2, v6
	v_lshl_add_u64 v[132:133], s[2:3], 0, v[4:5]
	v_readlane_b32 s2, v251, 1
	v_readlane_b32 s3, v251, 2
	v_add_u32_e32 v8, 0, v8
	v_lshlrev_b32_e32 v150, 12, v7
	v_lshl_add_u64 v[134:135], s[2:3], 0, v[4:5]
	v_lshlrev_b32_e32 v4, 6, v3
	v_lshlrev_b32_e32 v5, 6, v7
	v_and_or_b32 v149, v9, 12, v5
	v_lshlrev_b32_e32 v5, 6, v6
	v_add_u32_e32 v153, 0, v10
	v_add_u32_e32 v154, v8, v4
	v_and_b32_e32 v4, 3, v6
	v_and_b32_e32 v151, 0x3c0, v5
	v_and_b32_e32 v152, 0xffffe3c0, v5
	v_add_u32_e32 v7, v153, v150
	v_lshlrev_b32_e32 v4, 4, v4
	v_mov_b32_e32 v5, v2
	v_and_b32_e32 v148, 0xffffff8f, v6
	v_lshl_add_u64 v[136:137], s[2:3], 0, v[4:5]
	s_mov_b32 s2, 0
	v_add_u32_e32 v155, v7, v151
	s_mov_b32 s10, 0
	v_writelane_b32 v255, s20, 41
	v_writelane_b32 v255, s21, 42
	v_writelane_b32 v255, s22, 43
	v_writelane_b32 v255, s23, 44
	v_lshrrev_b32_e32 v4, 6, v1
	v_lshrrev_b32_e32 v5, 4, v1
	v_xor_b32_e32 v5, v5, v1
	v_readfirstlane_b32 s20, v4
	v_and_b32_e32 v5, 3, v5
	v_and_b32_e32 v4, 3, v1
	v_sub_u32_e32 v4, v5, v4
	v_lshlrev_b32_e32 v4, 4, v4
	v_ashrrev_i32_e32 v5, 31, v4
	s_lshl_b32 s20, s20, 10
	v_lshl_add_u64 v[132:133], v[132:133], 0, v[4:5]
	v_lshl_add_u64 v[134:135], v[134:135], 0, v[4:5]
	v_lshl_add_u64 v[136:137], v[136:137], 0, v[4:5]
	s_branch .LBB0_120

;     ...
;     const int m0 = tm * 256, n0 = tn * 128;
;     f32x4 acc[8][4];
; #pragma unroll
;     for (int i = 0; i < 8; ++i)
; #pragma unroll
;       for (int j = 0; j < 4; ++j) acc[i][j] = f32x4{0.f, 0.f, 0.f, 0.f};
;     u32x4 ra[4], rb[2];
;     const u16* Ag = A + (size_t)(m0 + ldrow) * K + ldp * 8 + kt0 * 32;
;     const u16* Bg = Bt + (size_t)(n0 + ldrow) * K + ldp * 8 + kt0 * 32;
; #pragma unroll
;     for (int i = 0; i < 4; ++i) ra[i] = *(const u32x4*)(Ag + (size_t)(i * 64) * K);
; #pragma unroll
;     for (int i = 0; i < 2; ++i) rb[i] = *(const u32x4*)(Bg + (size_t)(i * 64) * K);
;     __syncthreads();
; #pragma unroll
;     for (int i = 0; i < 4; ++i) *(u32x4*)(smem + (ldrow + i * 64) * 64 + lsw) = ra[i];
; #pragma unroll
;     for (int i = 0; i < 2; ++i) *(u32x4*)(smem + 16384 + (ldrow + i * 64) * 64 + lsw) = rb[i];
;     __syncthreads();
.LBB0_125:
	s_lshl_b32 s5, s6, 8
	v_add_u32_e32 v4, s5, v3
	v_ashrrev_i32_e32 v5, 31, v4
	v_lshlrev_b64 v[70:71], 12, v[4:5]
	v_lshl_add_u64 v[4:5], v[132:133], 0, v[70:71]
	v_add_co_u32_e32 v8, vcc, 0x40000, v4
	s_mov_b32 s2, 0x80000
	s_nop 0
	v_addc_co_u32_e32 v9, vcc, 0, v5, vcc
	v_add_u32_e32 v6, s4, v3
	v_add_co_u32_e32 v10, vcc, s2, v4
	v_ashrrev_i32_e32 v7, 31, v6
	s_nop 0
	v_addc_co_u32_e32 v11, vcc, 0, v5, vcc
	v_lshlrev_b64 v[6:7], 12, v[6:7]
	s_barrier
	s_add_u32 m0, s20, 0x1000
	s_nop 0
	global_load_lds_dwordx4 v[8:9], off
	s_add_u32 m0, s20, 0x6fc0
	s_nop 0
	global_load_lds_dwordx4 v[8:9], off offset:64
	s_add_u32 m0, s20, 0x2000
	s_nop 0
	global_load_lds_dwordx4 v[10:11], off
	s_add_u32 m0, s20, 0x7fc0
	s_nop 0
	global_load_lds_dwordx4 v[10:11], off offset:64
	v_add_co_u32_e32 v8, vcc, 0xc0000, v4
	v_lshl_add_u64 v[138:139], v[134:135], 0, v[6:7]
	s_nop 0
	v_addc_co_u32_e32 v9, vcc, 0, v5, vcc
	s_mov_b32 m0, s20
	s_nop 0
	global_load_lds_dwordx4 v[4:5], off
	s_add_u32 m0, s20, 0x5fc0
	s_nop 0
	global_load_lds_dwordx4 v[4:5], off offset:64
	s_add_u32 m0, s20, 0x4000
	s_nop 0
	global_load_lds_dwordx4 v[138:139], off
	s_add_u32 m0, s20, 0x9fc0
	s_nop 0
	global_load_lds_dwordx4 v[138:139], off offset:64
	v_add_co_u32_e32 v4, vcc, s11, v138
	s_mov_b32 s6, 0
	s_nop 0
	v_addc_co_u32_e32 v5, vcc, 0, v139, vcc
	s_add_u32 m0, s20, 0x3000
	s_nop 0
	global_load_lds_dwordx4 v[8:9], off
	s_add_u32 m0, s20, 0x8fc0
	s_nop 0
	global_load_lds_dwordx4 v[8:9], off offset:64
	s_add_u32 m0, s20, 0x5000
	s_nop 0
	global_load_lds_dwordx4 v[4:5], off
	s_add_u32 m0, s20, 0xafc0
	s_nop 0
	global_load_lds_dwordx4 v[4:5], off offset:64
	v_mov_b32_e32 v4, 0
	s_mov_b64 s[2:3], 0x80
	v_mov_b32_e32 v5, v4
	v_mov_b32_e32 v6, v4
	v_mov_b32_e32 v7, v4
	v_mov_b32_e32 v8, v4
	v_mov_b32_e32 v9, v4
	v_mov_b32_e32 v10, v4
	v_mov_b32_e32 v11, v4
	s_waitcnt vmcnt(21)
	v_mov_b32_e32 v12, v4
	v_mov_b32_e32 v13, v4
	v_mov_b32_e32 v14, v4
	v_mov_b32_e32 v15, v4
	v_mov_b32_e32 v16, v4
	v_mov_b32_e32 v17, v4
	v_mov_b32_e32 v18, v4
	v_mov_b32_e32 v19, v4
	s_waitcnt vmcnt(20)
	v_mov_b32_e32 v20, v4
	v_mov_b32_e32 v21, v4
	v_mov_b32_e32 v22, v4
	v_mov_b32_e32 v23, v4
	v_mov_b32_e32 v24, v4
	v_mov_b32_e32 v25, v4
	v_mov_b32_e32 v26, v4
	v_mov_b32_e32 v27, v4
	s_waitcnt vmcnt(19)
	v_mov_b32_e32 v28, v4
	v_mov_b32_e32 v29, v4
	v_mov_b32_e32 v30, v4
	v_mov_b32_e32 v31, v4
	s_waitcnt vmcnt(18)
	v_mov_b32_e32 v32, v4
	v_mov_b32_e32 v33, v4
	v_mov_b32_e32 v34, v4
	v_mov_b32_e32 v35, v4
	s_waitcnt vmcnt(16)
	v_mov_b32_e32 v36, v4
	v_mov_b32_e32 v37, v4
	v_mov_b32_e32 v38, v4
	v_mov_b32_e32 v39, v4
	s_waitcnt vmcnt(15)
	v_mov_b32_e32 v40, v4
	v_mov_b32_e32 v41, v4
	v_mov_b32_e32 v42, v4
	v_mov_b32_e32 v43, v4
	s_waitcnt vmcnt(14)
	v_mov_b32_e32 v44, v4
	v_lshl_add_u64 v[140:141], v[136:137], 0, v[70:71]
	v_mov_b32_e32 v45, v4
	v_mov_b32_e32 v70, v4
	v_mov_b32_e32 v71, v4
	v_mov_b32_e32 v72, v4
	v_mov_b32_e32 v73, v4
	v_mov_b32_e32 v74, v4
	v_mov_b32_e32 v75, v4
	v_mov_b32_e32 v76, v4
	v_mov_b32_e32 v77, v4
	v_mov_b32_e32 v78, v4
	v_mov_b32_e32 v79, v4
	v_mov_b32_e32 v80, v4
	v_mov_b32_e32 v81, v4
	v_mov_b32_e32 v82, v4
	v_mov_b32_e32 v83, v4
	v_mov_b32_e32 v84, v4
	v_mov_b32_e32 v46, v4
	v_mov_b32_e32 v47, v4
	v_mov_b32_e32 v48, v4
	v_mov_b32_e32 v49, v4
	v_mov_b32_e32 v50, v4
	v_mov_b32_e32 v51, v4
	v_mov_b32_e32 v52, v4
	v_mov_b32_e32 v53, v4
	v_mov_b32_e32 v54, v4
	v_mov_b32_e32 v55, v4
	v_mov_b32_e32 v56, v4
	v_mov_b32_e32 v57, v4
	v_mov_b32_e32 v58, v4
	v_mov_b32_e32 v59, v4
	v_mov_b32_e32 v60, v4
	v_mov_b32_e32 v61, v4
	v_mov_b32_e32 v62, v4
	v_mov_b32_e32 v63, v4
	v_mov_b32_e32 v64, v4
	v_mov_b32_e32 v65, v4
	v_mov_b32_e32 v66, v4
	v_mov_b32_e32 v67, v4
	v_mov_b32_e32 v68, v4
	v_mov_b32_e32 v69, v4
	v_mov_b32_e32 v85, v4
	v_mov_b32_e32 v86, v4
	v_mov_b32_e32 v87, v4
	v_mov_b32_e32 v88, v4
	v_mov_b32_e32 v89, v4
	v_mov_b32_e32 v90, v4
	v_mov_b32_e32 v91, v4
	v_mov_b32_e32 v92, v4
	v_mov_b32_e32 v93, v4
	v_mov_b32_e32 v94, v4
	v_mov_b32_e32 v95, v4
	v_mov_b32_e32 v96, v4
	v_mov_b32_e32 v97, v4
	v_mov_b32_e32 v98, v4
	v_mov_b32_e32 v99, v4
	v_mov_b32_e32 v100, v4
	v_mov_b32_e32 v101, v4
	v_mov_b32_e32 v102, v4
	v_mov_b32_e32 v103, v4
	v_mov_b32_e32 v104, v4
	v_mov_b32_e32 v105, v4
	v_mov_b32_e32 v106, v4
	v_mov_b32_e32 v107, v4
	v_mov_b32_e32 v108, v4
	v_mov_b32_e32 v109, v4
	v_mov_b32_e32 v110, v4
	v_mov_b32_e32 v111, v4
	v_mov_b32_e32 v112, v4
	v_mov_b32_e32 v113, v4
	v_mov_b32_e32 v114, v4
	v_mov_b32_e32 v115, v4
	v_mov_b32_e32 v116, v4
	v_mov_b32_e32 v117, v4
	v_mov_b32_e32 v118, v4
	v_mov_b32_e32 v119, v4
	v_mov_b32_e32 v120, v4
	v_mov_b32_e32 v121, v4
	v_mov_b32_e32 v122, v4
	v_mov_b32_e32 v123, v4
	v_mov_b32_e32 v124, v4
	v_mov_b32_e32 v125, v4
	v_mov_b32_e32 v126, v4
	v_mov_b32_e32 v127, v4
	v_mov_b32_e32 v128, v4
	v_mov_b32_e32 v129, v4
	v_mov_b32_e32 v130, v4
	v_mov_b32_e32 v131, v4
	s_mov_b32 s9, 0x2480000
	s_mov_b32 s12, 0x24c0000
	s_mov_b32 s13, 0x2500000
	s_mov_b32 s14, 0x2540000
	s_mov_b32 s21, 0
	s_mov_b32 s22, 0xc000
	s_waitcnt vmcnt(0) lgkmcnt(0)
	s_barrier
;     ...
;     for (int kt = 0; kt < nk; ++kt) {
;       const int buf = kt & 1;
;       if (kt + 1 < nk) {
; #pragma unroll
;         for (int i = 0; i < 4; ++i) ra[i] = *(const u32x4*)(Ag + (size_t)(i * 64) * K + (kt + 1) * 32);
; #pragma unroll
;         for (int i = 0; i < 2; ++i) rb[i] = *(const u32x4*)(Bg + (size_t)(i * 64) * K + (kt + 1) * 32);
;       }
;       const char* As = smem + buf * 24576;
;       const char* Bs = As + 16384;
;       bf16x8 bfr[4];
; #pragma unroll
;       for (int j = 0; j < 4; ++j) bfr[j] = *(const bf16x8*)(Bs + (wn * 64 + j * 16 + l15) * 64 + rsw);
;       bf16x8 afr[8];
; #pragma unroll
;       for (int i = 0; i < 8; ++i) afr[i] = *(const bf16x8*)(As + (wm * 128 + i * 16 + l15) * 64 + rsw);
;       __builtin_amdgcn_s_setprio(1);
; #pragma unroll
;       for (int i = 0; i < 8; ++i) {
; #pragma unroll
;         for (int j = 0; j < 4; ++j) acc[i][j] = __builtin_amdgcn_mfma_f32_16x16x32_bf16(bfr[j], afr[i], acc[i][j], 0, 0, 0);
;       }
;       __builtin_amdgcn_s_setprio(0);
;       if (kt + 1 < nk) {
;         char* Aw = smem + (buf ^ 1) * 24576;
;         char* Bw = Aw + 16384;
; #pragma unroll
;         for (int i = 0; i < 4; ++i) *(u32x4*)(Aw + (ldrow + i * 64) * 64 + lsw) = ra[i];
; #pragma unroll
;         for (int i = 0; i < 2; ++i) *(u32x4*)(Bw + (ldrow + i * 64) * 64 + lsw) = rb[i];
;       }
;       __syncthreads();
;     }
.LBB0_126:
	v_lshl_add_u64 v[142:143], v[140:141], 0, s[2:3]
	v_add_co_u32_e32 v156, vcc, s9, v142
	v_lshl_add_u64 v[146:147], v[138:139], 0, s[2:3]
	s_add_u32 s23, s22, s20
	v_addc_co_u32_e32 v157, vcc, 0, v143, vcc
	v_add_co_u32_e32 v160, vcc, s12, v142
	s_add_u32 m0, s23, 0x4000
	s_nop 0
	v_addc_co_u32_e32 v161, vcc, 0, v143, vcc
	v_add_co_u32_e32 v164, vcc, s13, v142
	s_add_i32 s6, s6, 1
	s_nop 0
	v_addc_co_u32_e32 v165, vcc, 0, v143, vcc
	v_add_co_u32_e32 v168, vcc, s14, v142
	s_nop 1
	v_addc_co_u32_e32 v169, vcc, 0, v143, vcc
	global_load_lds_dwordx4 v[146:147], off
	v_add_co_u32_e32 v146, vcc, s11, v146
	s_mov_b32 m0, s23
	s_nop 0
	v_addc_co_u32_e32 v147, vcc, 0, v147, vcc
	global_load_lds_dwordx4 v[156:157], off
	s_add_u32 m0, s23, 0x1000
	s_nop 0
	global_load_lds_dwordx4 v[160:161], off
	s_add_u32 m0, s23, 0x2000
	s_nop 0
	global_load_lds_dwordx4 v[164:165], off
	s_add_u32 m0, s23, 0x3000
	s_nop 0
	global_load_lds_dwordx4 v[168:169], off
	s_add_u32 m0, s23, 0x5000
	s_nop 0
	global_load_lds_dwordx4 v[146:147], off
	v_add_u32_e32 v146, s21, v153
	v_add3_u32 v147, v146, v150, v151
	v_add_u32_e32 v146, v146, v152
	ds_read_b128 v[176:179], v147 offset:16384
	ds_read_b128 v[180:183], v147 offset:17408
	ds_read_b128 v[184:187], v147 offset:18432
	ds_read_b128 v[188:191], v147 offset:19456
	ds_read_b128 v[192:195], v146
	ds_read_b128 v[196:199], v146 offset:1024
	ds_read_b128 v[230:233], v146 offset:2048
	ds_read_b128 v[234:237], v146 offset:3072
	ds_read_b128 v[238:241], v146 offset:4096
	ds_read_b128 v[242:245], v146 offset:5120
	ds_read_b128 v[246:249], v146 offset:6144
	ds_read_b128 v[220:223], v146 offset:7168
	s_setprio 1
	s_waitcnt lgkmcnt(7)
	v_mfma_f32_16x16x32_bf16 v[128:131], v[176:179], v[192:195], v[128:131]
	v_mfma_f32_16x16x32_bf16 v[124:127], v[180:183], v[192:195], v[124:127]
	v_mfma_f32_16x16x32_bf16 v[120:123], v[184:187], v[192:195], v[120:123]
	v_mfma_f32_16x16x32_bf16 v[116:119], v[188:191], v[192:195], v[116:119]
	s_waitcnt lgkmcnt(6)
	v_mfma_f32_16x16x32_bf16 v[112:115], v[176:179], v[196:199], v[112:115]
	v_mfma_f32_16x16x32_bf16 v[108:111], v[180:183], v[196:199], v[108:111]
	v_mfma_f32_16x16x32_bf16 v[104:107], v[184:187], v[196:199], v[104:107]
	v_mfma_f32_16x16x32_bf16 v[100:103], v[188:191], v[196:199], v[100:103]
	s_waitcnt lgkmcnt(5)
	v_mfma_f32_16x16x32_bf16 v[96:99], v[176:179], v[230:233], v[96:99]
	v_mfma_f32_16x16x32_bf16 v[92:95], v[180:183], v[230:233], v[92:95]
	v_mfma_f32_16x16x32_bf16 v[88:91], v[184:187], v[230:233], v[88:91]
	v_mfma_f32_16x16x32_bf16 v[84:87], v[188:191], v[230:233], v[84:87]
	s_waitcnt lgkmcnt(4)
	v_mfma_f32_16x16x32_bf16 v[80:83], v[176:179], v[234:237], v[80:83]
	v_mfma_f32_16x16x32_bf16 v[76:79], v[180:183], v[234:237], v[76:79]
	v_mfma_f32_16x16x32_bf16 v[72:75], v[184:187], v[234:237], v[72:75]
	v_mfma_f32_16x16x32_bf16 v[68:71], v[188:191], v[234:237], v[68:71]
	s_waitcnt lgkmcnt(3)
	v_mfma_f32_16x16x32_bf16 v[64:67], v[176:179], v[238:241], v[64:67]
	v_mfma_f32_16x16x32_bf16 v[60:63], v[180:183], v[238:241], v[60:63]
	v_mfma_f32_16x16x32_bf16 v[56:59], v[184:187], v[238:241], v[56:59]
	v_mfma_f32_16x16x32_bf16 v[52:55], v[188:191], v[238:241], v[52:55]
	s_waitcnt lgkmcnt(2)
	v_mfma_f32_16x16x32_bf16 v[48:51], v[176:179], v[242:245], v[48:51]
	v_mfma_f32_16x16x32_bf16 v[44:47], v[180:183], v[242:245], v[44:47]
	v_mfma_f32_16x16x32_bf16 v[40:43], v[184:187], v[242:245], v[40:43]
	v_mfma_f32_16x16x32_bf16 v[36:39], v[188:191], v[242:245], v[36:39]
	s_waitcnt lgkmcnt(1)
	v_mfma_f32_16x16x32_bf16 v[32:35], v[176:179], v[246:249], v[32:35]
	v_mfma_f32_16x16x32_bf16 v[28:31], v[180:183], v[246:249], v[28:31]
	v_mfma_f32_16x16x32_bf16 v[24:27], v[184:187], v[246:249], v[24:27]
	v_mfma_f32_16x16x32_bf16 v[20:23], v[188:191], v[246:249], v[20:23]
	s_waitcnt lgkmcnt(0)
	v_mfma_f32_16x16x32_bf16 v[16:19], v[176:179], v[220:223], v[16:19]
	v_mfma_f32_16x16x32_bf16 v[12:15], v[180:183], v[220:223], v[12:15]
	v_mfma_f32_16x16x32_bf16 v[8:11], v[184:187], v[220:223], v[8:11]
	v_mfma_f32_16x16x32_bf16 v[4:7], v[188:191], v[220:223], v[4:7]
	s_setprio 0
	s_add_u32 s2, s2, 64
	s_addc_u32 s3, s3, 0
	s_add_u32 s21, s21, 0x6000
	s_cmp_eq_u32 s21, 0x12000
	s_cselect_b32 s21, 0, s21
	s_add_u32 s22, s22, 0x6000
	s_cmp_eq_u32 s22, 0x12000
	s_cselect_b32 s22, 0, s22
	s_cmpk_eq_i32 s2, 0x1040
	s_waitcnt vmcnt(6)
	s_barrier
;     ...
;       const char* As = smem + buf * 24576;
;       const char* Bs = As + 16384;
;       bf16x8 bfr[4];
; #pragma unroll
;       for (int j = 0; j < 4; ++j) bfr[j] = *(const bf16x8*)(Bs + (wn * 64 + j * 16 + l15) * 64 + rsw);
;       bf16x8 afr[8];
; #pragma unroll
;       for (int i = 0; i < 8; ++i) afr[i] = *(const bf16x8*)(As + (wm * 128 + i * 16 + l15) * 64 + rsw);
;       __builtin_amdgcn_s_setprio(1);
; #pragma unroll
;       for (int i = 0; i < 8; ++i) {
; #pragma unroll
;         for (int j = 0; j < 4; ++j) acc[i][j] = __builtin_amdgcn_mfma_f32_16x16x32_bf16(bfr[j], afr[i], acc[i][j], 0, 0, 0);
;       }
;     ...
;     for (int i = 0; i < 8; ++i) {
;       const int row = m0 + wm * 128 + i * 16 + l15;
; #pragma unroll
;       for (int j = 0; j < 4; ++j) {
;         const int n = n0 + wn * 64 + j * 16 + quad * 4;
;         f32x4 a = acc[i][j];
;         if (EPI == EPI_Z) {
;           u16* dst;
;           if (n0 < 1536) dst = (u16*)(p.ws + W_ZA) + (size_t)row * LZA + n;
;           else if (n0 < 4736) dst = (u16*)(p.ws + W_ZB) + (size_t)row * LZB + (n - 1536);
;           else dst = (u16*)(p.ws + W_ZC) + (size_t)row * LZC + (n - 4736);
	s_cbranch_scc0 .LBB0_126
	v_add_u32_e32 v146, s21, v153
	v_add_u32_e32 v147, s21, v155
	v_add_u32_e32 v146, v146, v152
	ds_read_b128 v[138:141], v147 offset:16384
	ds_read_b128 v[142:145], v147 offset:17408
	ds_read_b128 v[156:159], v147 offset:18432
	ds_read_b128 v[160:163], v147 offset:19456
	ds_read_b128 v[164:167], v146
	ds_read_b128 v[168:171], v146 offset:1024
	ds_read_b128 v[172:175], v146 offset:2048
	ds_read_b128 v[176:179], v146 offset:3072
	ds_read_b128 v[180:183], v146 offset:4096
	ds_read_b128 v[184:187], v146 offset:5120
	ds_read_b128 v[188:191], v146 offset:6144
	ds_read_b128 v[192:195], v146 offset:7168
	s_setprio 1
	s_waitcnt lgkmcnt(7)
	v_mfma_f32_16x16x32_bf16 v[128:131], v[138:141], v[164:167], v[128:131]
	v_mfma_f32_16x16x32_bf16 v[124:127], v[142:145], v[164:167], v[124:127]
	v_mfma_f32_16x16x32_bf16 v[120:123], v[156:159], v[164:167], v[120:123]
	v_mfma_f32_16x16x32_bf16 v[116:119], v[160:163], v[164:167], v[116:119]
	s_waitcnt lgkmcnt(6)
	v_mfma_f32_16x16x32_bf16 v[112:115], v[138:141], v[168:171], v[112:115]
	v_mfma_f32_16x16x32_bf16 v[108:111], v[142:145], v[168:171], v[108:111]
	v_mfma_f32_16x16x32_bf16 v[104:107], v[156:159], v[168:171], v[104:107]
	v_mfma_f32_16x16x32_bf16 v[100:103], v[160:163], v[168:171], v[100:103]
	s_waitcnt lgkmcnt(5)
	v_mfma_f32_16x16x32_bf16 v[96:99], v[138:141], v[172:175], v[96:99]
	v_mfma_f32_16x16x32_bf16 v[92:95], v[142:145], v[172:175], v[92:95]
	v_mfma_f32_16x16x32_bf16 v[88:91], v[156:159], v[172:175], v[88:91]
	v_mfma_f32_16x16x32_bf16 v[84:87], v[160:163], v[172:175], v[84:87]
	s_waitcnt lgkmcnt(4)
	v_mfma_f32_16x16x32_bf16 v[80:83], v[138:141], v[176:179], v[80:83]
	v_mfma_f32_16x16x32_bf16 v[76:79], v[142:145], v[176:179], v[76:79]
	v_mfma_f32_16x16x32_bf16 v[72:75], v[156:159], v[176:179], v[72:75]
	v_mfma_f32_16x16x32_bf16 v[68:71], v[160:163], v[176:179], v[68:71]
	s_waitcnt lgkmcnt(3)
	v_mfma_f32_16x16x32_bf16 v[64:67], v[138:141], v[180:183], v[64:67]
	v_mfma_f32_16x16x32_bf16 v[60:63], v[142:145], v[180:183], v[60:63]
	v_mfma_f32_16x16x32_bf16 v[56:59], v[156:159], v[180:183], v[56:59]
	v_mfma_f32_16x16x32_bf16 v[52:55], v[160:163], v[180:183], v[52:55]
	s_waitcnt lgkmcnt(2)
	v_mfma_f32_16x16x32_bf16 v[48:51], v[138:141], v[184:187], v[48:51]
	v_mfma_f32_16x16x32_bf16 v[44:47], v[142:145], v[184:187], v[44:47]
	v_mfma_f32_16x16x32_bf16 v[40:43], v[156:159], v[184:187], v[40:43]
	v_mfma_f32_16x16x32_bf16 v[36:39], v[160:163], v[184:187], v[36:39]
	s_waitcnt lgkmcnt(1)
	v_mfma_f32_16x16x32_bf16 v[32:35], v[138:141], v[188:191], v[32:35]
	v_mfma_f32_16x16x32_bf16 v[28:31], v[142:145], v[188:191], v[28:31]
	v_mfma_f32_16x16x32_bf16 v[24:27], v[156:159], v[188:191], v[24:27]
	v_mfma_f32_16x16x32_bf16 v[20:23], v[160:163], v[188:191], v[20:23]
	s_waitcnt lgkmcnt(0)
	v_mfma_f32_16x16x32_bf16 v[16:19], v[138:141], v[192:195], v[16:19]
	v_mfma_f32_16x16x32_bf16 v[12:15], v[142:145], v[192:195], v[12:15]
	v_mfma_f32_16x16x32_bf16 v[8:11], v[156:159], v[192:195], v[8:11]
	v_mfma_f32_16x16x32_bf16 v[4:7], v[160:163], v[192:195], v[4:7]
	s_setprio 0
	s_cmpk_gt_i32 s4, 0x5ff
	v_add_u32_e32 v157, s5, v148
	v_add_u32_e32 v138, s4, v149
	s_cselect_b64 s[2:3], -1, 0
	s_cmpk_gt_u32 s4, 0x127f
	s_movk_i32 s4, 0x1400
	v_mad_i64_i32 v[142:143], s[4:5], v157, s4, 0
	s_movk_i32 s4, 0x1900
	s_nop 0
	v_mad_i64_i32 v[140:141], s[4:5], v157, s4, 0
	s_cselect_b64 s[6:7], -1, 0
	s_mov_b64 s[4:5], -1
	s_and_b64 vcc, exec, s[2:3]
	s_waitcnt vmcnt(0)
	s_barrier
	s_cbranch_vccz .LBB0_133
	v_mov_b32_e32 v139, v2
	s_and_b64 vcc, exec, s[6:7]
	s_cbranch_vccz .LBB0_130
	v_readlane_b32 s4, v251, 1
	v_readlane_b32 s5, v251, 2
	s_nop 1
	v_lshl_add_u64 v[144:145], s[4:5], 0, v[142:143]
	v_lshl_add_u64 v[144:145], v[138:139], 1, v[144:145]
	s_mov_b64 s[4:5], 0x1cfcdb00
	v_lshl_add_u64 v[146:147], v[144:145], 0, s[4:5]
	s_mov_b64 s[4:5], 0

; __global__ void __launch_bounds__(256, 2) mega(Params p) {
;     ...
;     gemm_phase<EPI_Z>(p, l, (const u16*)(p.ws + W_XN), (const u16*)(p.ws + W_WTIN), D, NIN / 128, smem, bid, nb, false);
;     grid.sync();
.LBB0_383:
	v_readlane_b32 s20, v255, 41
	v_readlane_b32 s21, v255, 42
	v_readlane_b32 s22, v255, 43
	v_readlane_b32 s23, v255, 44
	s_waitcnt vmcnt(0)
	s_barrier
	s_mov_b64 s[2:3], exec
	v_readlane_b32 s4, v254, 0
	v_readlane_b32 s5, v254, 1
	s_and_b64 s[4:5], s[2:3], s[4:5]
	s_mov_b64 exec, s[4:5]
	s_cbranch_execz .LBB0_393
	v_readlane_b32 s4, v251, 1
	v_readlane_b32 s5, v251, 2
	v_readlane_b32 s8, v251, 5
	v_readlane_b32 s9, v251, 0
	buffer_wbl2 sc1
	s_waitcnt vmcnt(0)
	s_add_u32 s4, s4, 0x318aa000
	s_addc_u32 s5, s5, 0
	v_mov_b32_e32 v3, 1
	v_mov_b32_e32 v4, 0x500
	s_and_b32 s9, s9, 7
	s_lshl_b32 s9, s9, 8
	s_add_u32 s9, s9, 0x8800
	global_atomic_add v3, v4, v3, s[4:5] sc0
	v_mov_b32_e32 v5, s9
	s_waitcnt vmcnt(0)
	v_readfirstlane_b32 s10, v3
	s_mov_b32 s11, s8

; DEVI float bf2f(u32 h) { return __uint_as_float(h << 16); }
; DEVI void gd_chain_task(const Params& p, int l, int seq, int h, int vhalf, char* smem) {
;     ...
;     bf16x8 Sb[4];
; #pragma unroll
;     for (int kk = 0; kk < 4; ++kk) Sb[kk] = pk8(Sacc[2 * kk], Sacc[2 * kk + 1]);
;     f32x4 vn[4];
; #pragma unroll
;     for (int mt = 0; mt < 4; ++mt) {
; #pragma unroll
;       for (int r = 0; r < 4; ++r) vn[mt][r] = bf2f(*(const u16*)(smem + U_OFF + (mt * 16 + quad * 4 + r) * 144 + (wave * 16 + l15) * 2));
;       const char* wr = smem + W_OFF + (mt * 16 + l15) * 272 + quad * 8;
; #pragma unroll
;       for (int kk = 0; kk < 4; ++kk) {
;         bf16x8 a = mk8(*(const uint2*)(wr + kk * 64), *(const uint2*)(wr + kk * 64 + 32));
;         vn[mt] = __builtin_amdgcn_mfma_f32_16x16x32_bf16(a, Sb[kk], vn[mt], 0, 0, 0);
;       }
;     }
;     bf16x8 Vb[2];
;     Vb[0] = pk8(vn[0], vn[1]);
;     Vb[1] = pk8(vn[2], vn[3]);
; #pragma unroll
;     for (int mt = 0; mt < 4; ++mt) {
;       if (mt * 16 < ntok) {
;         f32x4 o = f32x4{0.f, 0.f, 0.f, 0.f};
;         const char* qr = smem + Q_OFF + (mt * 16 + l15) * 272 + quad * 8;
; #pragma unroll
;         for (int kk = 0; kk < 4; ++kk) {
;           bf16x8 a = mk8(*(const uint2*)(qr + kk * 64), *(const uint2*)(qr + kk * 64 + 32));
;           o = __builtin_amdgcn_mfma_f32_16x16x32_bf16(a, Sb[kk], o, 0, 0, 0);
.LBB0_972:
	s_mov_b32 s20, 0xffff0000
	v_cvt_pk_bf16_f32 v110, v98, v99
	v_cvt_pk_bf16_f32 v111, v100, v101
	v_cvt_pk_bf16_f32 v112, v50, v51
	v_cvt_pk_bf16_f32 v113, v52, v53
	v_cvt_pk_bf16_f32 v114, v94, v95
	v_cvt_pk_bf16_f32 v115, v96, v97
	v_cvt_pk_bf16_f32 v116, v90, v91
	v_cvt_pk_bf16_f32 v117, v92, v93
	v_cvt_pk_bf16_f32 v122, v78, v79
	v_cvt_pk_bf16_f32 v123, v80, v81
	v_cvt_pk_bf16_f32 v124, v82, v83
	v_cvt_pk_bf16_f32 v125, v84, v85
	v_cvt_pk_bf16_f32 v118, v74, v75
	v_cvt_pk_bf16_f32 v119, v76, v77
	v_cvt_pk_bf16_f32 v120, v86, v87
	v_cvt_pk_bf16_f32 v121, v88, v89
	ds_read_u16 v3, v180 offset:62464
	ds_read2_b64 v[106:109], v182 offset1:4
	v_pk_mul_f32 v[100:101], v[130:131], v[100:101] op_sel_hi:[0,1]
	v_pk_mul_f32 v[98:99], v[130:131], v[98:99] op_sel_hi:[0,1]
	v_pk_mul_f32 v[52:53], v[130:131], v[52:53] op_sel_hi:[0,1]
	s_waitcnt lgkmcnt(1)
	v_lshlrev_b32_e32 v102, 16, v3
	ds_read_u16 v3, v181 offset:62464
	v_pk_mul_f32 v[50:51], v[130:131], v[50:51] op_sel_hi:[0,1]
	v_pk_mul_f32 v[96:97], v[130:131], v[96:97] op_sel_hi:[0,1]
	v_pk_mul_f32 v[94:95], v[130:131], v[94:95] op_sel_hi:[0,1]
	v_pk_mul_f32 v[92:93], v[130:131], v[92:93] op_sel_hi:[0,1]
	s_waitcnt lgkmcnt(0)
	v_lshlrev_b32_e32 v103, 16, v3
	ds_read_u16 v3, v181 offset:62608
	v_pk_mul_f32 v[90:91], v[130:131], v[90:91] op_sel_hi:[0,1]
	v_pk_mul_f32 v[80:81], v[130:131], v[80:81] op_sel_hi:[0,1]
	v_pk_mul_f32 v[78:79], v[130:131], v[78:79] op_sel_hi:[0,1]
	v_pk_mul_f32 v[84:85], v[130:131], v[84:85] op_sel_hi:[0,1]
	s_waitcnt lgkmcnt(0)
	v_lshlrev_b32_e32 v104, 16, v3
	ds_read_u16 v3, v181 offset:62752
	v_pk_mul_f32 v[82:83], v[130:131], v[82:83] op_sel_hi:[0,1]
	v_pk_mul_f32 v[76:77], v[130:131], v[76:77] op_sel_hi:[0,1]
	v_pk_mul_f32 v[74:75], v[130:131], v[74:75] op_sel_hi:[0,1]
	v_pk_mul_f32 v[88:89], v[130:131], v[88:89] op_sel_hi:[0,1]
	s_waitcnt lgkmcnt(0)
	v_lshlrev_b32_e32 v105, 16, v3
	ds_read_u16 v3, v181 offset:64624
	v_pk_mul_f32 v[86:87], v[130:131], v[86:87] op_sel_hi:[0,1]
	v_mfma_f32_16x16x32_bf16 v[102:105], v[106:109], v[110:113], v[102:105]
	ds_read2_b64 v[106:109], v182 offset0:8 offset1:12
	s_waitcnt lgkmcnt(0)
	v_mfma_f32_16x16x32_bf16 v[102:105], v[106:109], v[114:117], v[102:105]
	ds_read2_b64 v[106:109], v182 offset0:16 offset1:20
	s_waitcnt lgkmcnt(0)
	v_mfma_f32_16x16x32_bf16 v[102:105], v[106:109], v[122:125], v[102:105]
	ds_read2_b64 v[106:109], v182 offset0:24 offset1:28
	s_waitcnt lgkmcnt(0)
	v_mfma_f32_16x16x32_bf16 v[102:105], v[106:109], v[118:121], v[102:105]
	v_lshlrev_b32_e32 v106, 16, v3
	ds_read_u16 v3, v181 offset:64768
	s_nop 5
	s_waitcnt lgkmcnt(0)
	v_lshlrev_b32_e32 v107, 16, v3
	ds_read_u16 v3, v183 offset:62464
	s_waitcnt lgkmcnt(0)
	v_lshlrev_b32_e32 v108, 16, v3
	ds_read_u16 v3, v183 offset:62608
	s_waitcnt lgkmcnt(0)
	v_lshlrev_b32_e32 v109, 16, v3
	v_add_u32_e32 v3, 0x1000, v182
	ds_read2_b64 v[126:129], v3 offset0:32 offset1:36
	s_waitcnt lgkmcnt(0)
	v_mfma_f32_16x16x32_bf16 v[106:109], v[126:129], v[110:113], v[106:109]
	ds_read2_b64 v[126:129], v3 offset0:40 offset1:44
	s_waitcnt lgkmcnt(0)
	v_mfma_f32_16x16x32_bf16 v[106:109], v[126:129], v[114:117], v[106:109]
	ds_read2_b64 v[126:129], v3 offset0:48 offset1:52
	s_waitcnt lgkmcnt(0)
	v_mfma_f32_16x16x32_bf16 v[106:109], v[126:129], v[122:125], v[106:109]
	ds_read2_b64 v[126:129], v3 offset0:56 offset1:60
	ds_read_u16 v3, v183 offset:64480
	s_waitcnt lgkmcnt(1)
	v_mfma_f32_16x16x32_bf16 v[126:129], v[126:129], v[118:121], v[106:109]
	s_waitcnt lgkmcnt(0)
	s_nop 2
	v_lshlrev_b32_e32 v106, 16, v3
	ds_read_u16 v3, v183 offset:64624
	s_waitcnt lgkmcnt(0)
	v_lshlrev_b32_e32 v107, 16, v3
	ds_read_u16 v3, v183 offset:64768
	s_waitcnt lgkmcnt(0)
	v_lshlrev_b32_e32 v108, 16, v3
	ds_read_u16 v3, v183 offset:64912
	s_waitcnt lgkmcnt(0)
	v_lshlrev_b32_e32 v109, 16, v3
	v_add_u32_e32 v3, 0x2000, v182
	ds_read2_b64 v[188:191], v3 offset0:64 offset1:68
	s_waitcnt lgkmcnt(0)
	v_mfma_f32_16x16x32_bf16 v[106:109], v[188:191], v[110:113], v[106:109]
	ds_read2_b64 v[188:191], v3 offset0:72 offset1:76
	s_waitcnt lgkmcnt(0)
	v_mfma_f32_16x16x32_bf16 v[106:109], v[188:191], v[114:117], v[106:109]
	ds_read2_b64 v[188:191], v3 offset0:80 offset1:84
	s_waitcnt lgkmcnt(0)
	v_mfma_f32_16x16x32_bf16 v[106:109], v[188:191], v[122:125], v[106:109]
	ds_read2_b64 v[188:191], v3 offset0:88 offset1:92
	ds_read_u16 v3, v184 offset:64768
	s_waitcnt lgkmcnt(1)
	v_mfma_f32_16x16x32_bf16 v[188:191], v[188:191], v[118:121], v[106:109]
	s_waitcnt lgkmcnt(0)
	s_nop 2
	v_lshlrev_b32_e32 v106, 16, v3
	ds_read_u16 v3, v184 offset:64912
	s_waitcnt lgkmcnt(0)
	v_lshlrev_b32_e32 v107, 16, v3
	ds_read_u16 v3, v184 offset:65056
	s_waitcnt lgkmcnt(0)
	v_lshlrev_b32_e32 v108, 16, v3
	ds_read_u16 v3, v184 offset:65200
	s_waitcnt lgkmcnt(0)
	v_lshlrev_b32_e32 v109, 16, v3
	v_add_u32_e32 v3, 0x3000, v182
	ds_read2_b64 v[192:195], v3 offset0:96 offset1:100
	s_waitcnt lgkmcnt(0)
	v_mfma_f32_16x16x32_bf16 v[106:109], v[192:195], v[110:113], v[106:109]
	ds_read2_b64 v[192:195], v3 offset0:104 offset1:108
	s_waitcnt lgkmcnt(0)
	v_mfma_f32_16x16x32_bf16 v[106:109], v[192:195], v[114:117], v[106:109]
	ds_read2_b64 v[192:195], v3 offset0:112 offset1:116
	s_waitcnt lgkmcnt(0)
	v_mfma_f32_16x16x32_bf16 v[106:109], v[192:195], v[122:125], v[106:109]
	ds_read2_b64 v[192:195], v3 offset0:120 offset1:124
	s_waitcnt lgkmcnt(0)
	v_mfma_f32_16x16x32_bf16 v[192:195], v[192:195], v[118:121], v[106:109]
	s_nop 2
	s_nop 1
	v_cvt_pk_bf16_f32 v106, v102, v103
	v_cvt_pk_bf16_f32 v107, v104, v105
	v_cvt_pk_bf16_f32 v108, v126, v127
	v_cvt_pk_bf16_f32 v109, v128, v129
	v_cvt_pk_bf16_f32 v102, v188, v189
	v_cvt_pk_bf16_f32 v103, v190, v191
	v_cvt_pk_bf16_f32 v104, v192, v193
	v_cvt_pk_bf16_f32 v105, v194, v195
	v_add_u32_e32 v3, 0x4000, v182
	ds_read2_b64 v[126:129], v3 offset0:128 offset1:132
	ds_read2_b64 v[188:191], v3 offset0:136 offset1:140
	s_waitcnt lgkmcnt(1)
; DEVI u32 f2bf(float f) { u32 u = __float_as_uint(f); return (u + 0x7fffu + ((u >> 16) & 1u)) >> 16; }
; DEVI void gd_chain_task(const Params& p, int l, int seq, int h, int vhalf, char* smem) {
;     ...
;     for (int mt = 0; mt < 4; ++mt) {
;       if (mt * 16 < ntok) {
;         f32x4 o = f32x4{0.f, 0.f, 0.f, 0.f};
;         const char* qr = smem + Q_OFF + (mt * 16 + l15) * 272 + quad * 8;
; #pragma unroll
;         for (int kk = 0; kk < 4; ++kk) {
;           bf16x8 a = mk8(*(const uint2*)(qr + kk * 64), *(const uint2*)(qr + kk * 64 + 32));
;           o = __builtin_amdgcn_mfma_f32_16x16x32_bf16(a, Sb[kk], o, 0, 0, 0);
;         }
;         const char* ir = smem + I_OFF + (mt * 16 + l15) * 144 + quad * 8;
; #pragma unroll
;         for (int k2 = 0; k2 < 2; ++k2) {
;           bf16x8 a = mk8(*(const uint2*)(ir + k2 * 64), *(const uint2*)(ir + k2 * 64 + 32));
;           o = __builtin_amdgcn_mfma_f32_16x16x32_bf16(a, Vb[k2], o, 0, 0, 0);
;         }
; #pragma unroll
;         for (int r = 0; r < 4; ++r) {
;           int c = mt * 16 + quad * 4 + r;
;           cat[(g0 + c) * D + 512 + h * 128 + vcol] = (u16)f2bf(o[r]);
;         }
	v_mfma_f32_16x16x32_bf16 v[126:129], v[126:129], v[110:113], 0
	v_readlane_b32 s20, v253, 27
	v_readlane_b32 s21, v253, 28
	s_waitcnt lgkmcnt(0)
	v_mfma_f32_16x16x32_bf16 v[126:129], v[188:191], v[114:117], v[126:129]
	ds_read2_b64 v[188:191], v3 offset0:144 offset1:148
	v_lshl_add_u64 v[4:5], s[20:21], 0, v[166:167]
	v_readlane_b32 s20, v251, 1
	s_waitcnt lgkmcnt(0)
	v_mfma_f32_16x16x32_bf16 v[126:129], v[188:191], v[122:125], v[126:129]
	ds_read2_b64 v[188:191], v3 offset0:152 offset1:156
	v_add_u32_e32 v3, 0x8800, v185
	v_readlane_b32 s21, v251, 2
	s_waitcnt lgkmcnt(0)
	v_mfma_f32_16x16x32_bf16 v[126:129], v[188:191], v[118:121], v[126:129]
	ds_read2_b64 v[188:191], v3 offset1:4
	s_waitcnt lgkmcnt(0)
	v_mfma_f32_16x16x32_bf16 v[126:129], v[188:191], v[106:109], v[126:129]
	ds_read2_b64 v[188:191], v3 offset0:8 offset1:12
	s_waitcnt lgkmcnt(0)
	v_mfma_f32_16x16x32_bf16 v[126:129], v[188:191], v[102:105], v[126:129]
	s_nop 7
	v_bfe_u32 v3, v126, 16, 1
	v_add3_u32 v3, v126, v3, s33
	global_store_short_d16_hi v[4:5], v3, off
	v_lshl_add_u64 v[4:5], s[20:21], 0, v[164:165]
	s_mov_b32 s20, 0x2481000
	v_bfe_u32 v3, v127, 16, 1
	v_add_co_u32_e32 v126, vcc, s20, v4
	v_add3_u32 v3, v127, v3, s33
	s_nop 0
	v_addc_co_u32_e32 v127, vcc, 0, v5, vcc
	s_mov_b32 s20, 0x2482000
	global_store_short_d16_hi v[126:127], v3, off offset:1024
	v_bfe_u32 v3, v128, 16, 1
	v_add_co_u32_e32 v126, vcc, s20, v4
	v_add3_u32 v3, v128, v3, s33
	s_nop 0
	v_addc_co_u32_e32 v127, vcc, 0, v5, vcc
	s_mov_b32 s20, 0x2483000
	global_store_short_d16_hi v[126:127], v3, off offset:1024
	v_bfe_u32 v3, v129, 16, 1
	v_add_co_u32_e32 v126, vcc, s20, v4
	v_add3_u32 v3, v129, v3, s33
	s_nop 0
	v_addc_co_u32_e32 v127, vcc, 0, v5, vcc
	global_store_short_d16_hi v[126:127], v3, off offset:1024
	v_add_u32_e32 v3, 0x5000, v182
	ds_read2_b64 v[126:129], v3 offset0:160 offset1:164
	ds_read2_b64 v[188:191], v3 offset0:168 offset1:172
	s_waitcnt lgkmcnt(1)
	v_mfma_f32_16x16x32_bf16 v[126:129], v[126:129], v[110:113], 0
	s_mov_b32 s20, 0x2490000
	s_waitcnt lgkmcnt(0)
	v_mfma_f32_16x16x32_bf16 v[126:129], v[188:191], v[114:117], v[126:129]
	ds_read2_b64 v[188:191], v3 offset0:176 offset1:180
	s_waitcnt lgkmcnt(0)
	v_mfma_f32_16x16x32_bf16 v[126:129], v[188:191], v[122:125], v[126:129]
	ds_read2_b64 v[188:191], v3 offset0:184 offset1:188
	v_add_u32_e32 v3, 0x9000, v185
	s_waitcnt lgkmcnt(0)
	v_mfma_f32_16x16x32_bf16 v[126:129], v[188:191], v[118:121], v[126:129]
	ds_read2_b64 v[188:191], v3 offset0:32 offset1:36
	s_waitcnt lgkmcnt(0)
	v_mfma_f32_16x16x32_bf16 v[126:129], v[188:191], v[106:109], v[126:129]
	ds_read2_b64 v[188:191], v3 offset0:40 offset1:44
	s_waitcnt lgkmcnt(0)
	v_mfma_f32_16x16x32_bf16 v[126:129], v[188:191], v[102:105], v[126:129]
	v_add_co_u32_e32 v188, vcc, s20, v4
	s_mov_b32 s20, 0x2491000
	s_nop 5
	v_bfe_u32 v3, v126, 16, 1
	v_add3_u32 v3, v126, v3, s33
	v_addc_co_u32_e32 v189, vcc, 0, v5, vcc
	global_store_short_d16_hi v[188:189], v3, off offset:1024
	v_bfe_u32 v3, v127, 16, 1
	v_add_co_u32_e32 v126, vcc, s20, v4
	v_add3_u32 v3, v127, v3, s33
	s_nop 0
	v_addc_co_u32_e32 v127, vcc, 0, v5, vcc
	s_mov_b32 s20, 0x2492000
	global_store_short_d16_hi v[126:127], v3, off offset:1024
	v_bfe_u32 v3, v128, 16, 1
	v_add_co_u32_e32 v126, vcc, s20, v4
	v_add3_u32 v3, v128, v3, s33
	s_nop 0
	v_addc_co_u32_e32 v127, vcc, 0, v5, vcc
	s_mov_b32 s20, 0x2493000
	global_store_short_d16_hi v[126:127], v3, off offset:1024
	v_bfe_u32 v3, v129, 16, 1
	v_add_co_u32_e32 v126, vcc, s20, v4
	v_add3_u32 v3, v129, v3, s33
	s_nop 0
	v_addc_co_u32_e32 v127, vcc, 0, v5, vcc
	global_store_short_d16_hi v[126:127], v3, off offset:1024
	v_add_u32_e32 v3, 0x6000, v182
	ds_read2_b64 v[126:129], v3 offset0:192 offset1:196
	ds_read2_b64 v[188:191], v3 offset0:200 offset1:204
	s_waitcnt lgkmcnt(1)
	v_mfma_f32_16x16x32_bf16 v[126:129], v[126:129], v[110:113], 0
	s_mov_b32 s20, 0x24a0000
	s_waitcnt lgkmcnt(0)
	v_mfma_f32_16x16x32_bf16 v[126:129], v[188:191], v[114:117], v[126:129]
	ds_read2_b64 v[188:191], v3 offset0:208 offset1:212
	s_waitcnt lgkmcnt(0)
	v_mfma_f32_16x16x32_bf16 v[126:129], v[188:191], v[122:125], v[126:129]
	ds_read2_b64 v[188:191], v3 offset0:216 offset1:220
	v_add_u32_e32 v3, 0x9800, v185
	s_waitcnt lgkmcnt(0)
	v_mfma_f32_16x16x32_bf16 v[126:129], v[188:191], v[118:121], v[126:129]
	ds_read2_b64 v[188:191], v3 offset0:64 offset1:68
	s_waitcnt lgkmcnt(0)
	v_mfma_f32_16x16x32_bf16 v[126:129], v[188:191], v[106:109], v[126:129]
	ds_read2_b64 v[188:191], v3 offset0:72 offset1:76
	s_waitcnt lgkmcnt(0)
	v_mfma_f32_16x16x32_bf16 v[126:129], v[188:191], v[102:105], v[126:129]
	v_add_co_u32_e32 v188, vcc, s20, v4
	s_mov_b32 s20, 0x24a1000
	s_nop 5
	v_bfe_u32 v3, v126, 16, 1
	v_add3_u32 v3, v126, v3, s33
	v_addc_co_u32_e32 v189, vcc, 0, v5, vcc
	global_store_short_d16_hi v[188:189], v3, off offset:1024
	v_bfe_u32 v3, v127, 16, 1
	v_add_co_u32_e32 v126, vcc, s20, v4
	v_add3_u32 v3, v127, v3, s33
	s_nop 0
	v_addc_co_u32_e32 v127, vcc, 0, v5, vcc
	s_mov_b32 s20, 0x24a2000
	global_store_short_d16_hi v[126:127], v3, off offset:1024
	v_bfe_u32 v3, v128, 16, 1
	v_add_co_u32_e32 v126, vcc, s20, v4
	v_add3_u32 v3, v128, v3, s33
	s_nop 0
	v_addc_co_u32_e32 v127, vcc, 0, v5, vcc
	s_mov_b32 s20, 0x24a3000
	global_store_short_d16_hi v[126:127], v3, off offset:1024
	v_bfe_u32 v3, v129, 16, 1
	v_add_co_u32_e32 v126, vcc, s20, v4
	v_add3_u32 v3, v129, v3, s33
	s_nop 0
	v_addc_co_u32_e32 v127, vcc, 0, v5, vcc
	global_store_short_d16_hi v[126:127], v3, off offset:1024
	v_add_u32_e32 v3, 0x7000, v182
	ds_read2_b64 v[126:129], v3 offset0:224 offset1:228
	s_waitcnt lgkmcnt(0)
; DEVI u32 f2bf(float f) { u32 u = __float_as_uint(f); return (u + 0x7fffu + ((u >> 16) & 1u)) >> 16; }
; DEVI void gd_chain_task(const Params& p, int l, int seq, int h, int vhalf, char* smem) {
;     ...
;     for (int mt = 0; mt < 4; ++mt) {
;       if (mt * 16 < ntok) {
;         f32x4 o = f32x4{0.f, 0.f, 0.f, 0.f};
;         const char* qr = smem + Q_OFF + (mt * 16 + l15) * 272 + quad * 8;
; #pragma unroll
;         for (int kk = 0; kk < 4; ++kk) {
;           bf16x8 a = mk8(*(const uint2*)(qr + kk * 64), *(const uint2*)(qr + kk * 64 + 32));
;           o = __builtin_amdgcn_mfma_f32_16x16x32_bf16(a, Sb[kk], o, 0, 0, 0);
;         }
;         const char* ir = smem + I_OFF + (mt * 16 + l15) * 144 + quad * 8;
; #pragma unroll
;         for (int k2 = 0; k2 < 2; ++k2) {
;           bf16x8 a = mk8(*(const uint2*)(ir + k2 * 64), *(const uint2*)(ir + k2 * 64 + 32));
;           o = __builtin_amdgcn_mfma_f32_16x16x32_bf16(a, Vb[k2], o, 0, 0, 0);
;         }
; #pragma unroll
;         for (int r = 0; r < 4; ++r) {
;           int c = mt * 16 + quad * 4 + r;
;           cat[(g0 + c) * D + 512 + h * 128 + vcol] = (u16)f2bf(o[r]);
;         }
;       }
;     }
; #pragma unroll
;     for (int kt = 0; kt < 8; ++kt) {
;       f32x4 s = Sacc[kt];
;       s[0] *= egl; s[1] *= egl; s[2] *= egl; s[3] *= egl;
;       const char* kr = smem + K_OFF + (kt * 16 + l15) * 144 + quad * 8;
; #pragma unroll
;       for (int k2 = 0; k2 < 2; ++k2) {
;         bf16x8 a = mk8(*(const uint2*)(kr + k2 * 64), *(const uint2*)(kr + k2 * 64 + 32));
;         s = __builtin_amdgcn_mfma_f32_16x16x32_bf16(a, Vb[k2], s, 0, 0, 0);
;       }
;       Sacc[kt] = s;
;     }
;     lds_barrier();
;     if (cc + 1 < nchunk) GD_STORE();
;     lds_barrier();
	v_mfma_f32_16x16x32_bf16 v[110:113], v[126:129], v[110:113], 0
	ds_read2_b64 v[126:129], v3 offset0:232 offset1:236
	s_mov_b32 s20, 0x24b0000
	s_waitcnt lgkmcnt(0)
	v_mfma_f32_16x16x32_bf16 v[110:113], v[126:129], v[114:117], v[110:113]
	ds_read2_b64 v[114:117], v3 offset0:240 offset1:244
	s_waitcnt lgkmcnt(0)
	v_mfma_f32_16x16x32_bf16 v[110:113], v[114:117], v[122:125], v[110:113]
	ds_read2_b64 v[114:117], v3 offset0:248 offset1:252
	v_add_u32_e32 v3, 0xa000, v185
	s_waitcnt lgkmcnt(0)
	v_mfma_f32_16x16x32_bf16 v[110:113], v[114:117], v[118:121], v[110:113]
	ds_read2_b64 v[114:117], v3 offset0:96 offset1:100
	s_waitcnt lgkmcnt(0)
	v_mfma_f32_16x16x32_bf16 v[110:113], v[114:117], v[106:109], v[110:113]
	ds_read2_b64 v[114:117], v3 offset0:104 offset1:108
	s_waitcnt lgkmcnt(0)
	v_mfma_f32_16x16x32_bf16 v[110:113], v[114:117], v[102:105], v[110:113]
	v_add_co_u32_e32 v114, vcc, s20, v4
	s_mov_b32 s20, 0x24b1000
	s_nop 5
	v_bfe_u32 v3, v110, 16, 1
	v_add3_u32 v3, v110, v3, s33
	v_addc_co_u32_e32 v115, vcc, 0, v5, vcc
	global_store_short_d16_hi v[114:115], v3, off offset:1024
	v_bfe_u32 v3, v111, 16, 1
	v_add_co_u32_e32 v110, vcc, s20, v4
	v_add3_u32 v3, v111, v3, s33
	s_nop 0
	v_addc_co_u32_e32 v111, vcc, 0, v5, vcc
	s_mov_b32 s20, 0x24b2000
	global_store_short_d16_hi v[110:111], v3, off offset:1024
	v_bfe_u32 v3, v112, 16, 1
	v_add_co_u32_e32 v110, vcc, s20, v4
	v_add3_u32 v3, v112, v3, s33
	s_nop 0
	v_addc_co_u32_e32 v111, vcc, 0, v5, vcc
	s_mov_b32 s20, 0x24b3000
	global_store_short_d16_hi v[110:111], v3, off offset:1024
	v_bfe_u32 v3, v113, 16, 1
	v_add_co_u32_e32 v4, vcc, s20, v4
	v_add3_u32 v3, v113, v3, s33
	s_nop 0
	v_addc_co_u32_e32 v5, vcc, 0, v5, vcc
	global_store_short_d16_hi v[4:5], v3, off offset:1024
	v_add_u32_e32 v3, 0xa800, v185
	ds_read2_b64 v[110:113], v3 offset0:128 offset1:132
	s_waitcnt lgkmcnt(0)
	v_mfma_f32_16x16x32_bf16 v[98:101], v[110:113], v[106:109], v[98:101]
	ds_read2_b64 v[110:113], v3 offset0:136 offset1:140
	v_add_u32_e32 v3, 0xb000, v185
	s_andn2_b64 vcc, exec, s[18:19]
	s_waitcnt lgkmcnt(0)
	v_mfma_f32_16x16x32_bf16 v[98:101], v[110:113], v[102:105], v[98:101]
	ds_read2_b64 v[110:113], v3 offset0:160 offset1:164
	s_waitcnt lgkmcnt(0)
	v_mfma_f32_16x16x32_bf16 v[50:53], v[110:113], v[106:109], v[50:53]
	ds_read2_b64 v[110:113], v3 offset0:168 offset1:172
	v_add_u32_e32 v3, 0xb800, v185
	s_waitcnt lgkmcnt(0)
	v_mfma_f32_16x16x32_bf16 v[50:53], v[110:113], v[102:105], v[50:53]
	ds_read2_b64 v[110:113], v3 offset0:192 offset1:196
	s_waitcnt lgkmcnt(0)
	v_mfma_f32_16x16x32_bf16 v[94:97], v[110:113], v[106:109], v[94:97]
	ds_read2_b64 v[110:113], v3 offset0:200 offset1:204
	v_add_u32_e32 v3, 0xc000, v185
	s_waitcnt lgkmcnt(0)
	v_mfma_f32_16x16x32_bf16 v[94:97], v[110:113], v[102:105], v[94:97]
	ds_read2_b64 v[110:113], v3 offset0:224 offset1:228
	s_waitcnt lgkmcnt(0)
	v_mfma_f32_16x16x32_bf16 v[90:93], v[110:113], v[106:109], v[90:93]
	ds_read2_b64 v[110:113], v3 offset0:232 offset1:236
	v_add_u32_e32 v3, 0xd000, v185
	s_waitcnt lgkmcnt(0)
	v_mfma_f32_16x16x32_bf16 v[90:93], v[110:113], v[102:105], v[90:93]
	ds_read2_b64 v[110:113], v3 offset1:4
	s_waitcnt lgkmcnt(0)
	v_mfma_f32_16x16x32_bf16 v[78:81], v[110:113], v[106:109], v[78:81]
	ds_read2_b64 v[110:113], v3 offset0:8 offset1:12
	v_add_u32_e32 v3, 0xd800, v185
	s_waitcnt lgkmcnt(0)
	v_mfma_f32_16x16x32_bf16 v[78:81], v[110:113], v[102:105], v[78:81]
	ds_read2_b64 v[110:113], v3 offset0:32 offset1:36
	s_waitcnt lgkmcnt(0)
	v_mfma_f32_16x16x32_bf16 v[82:85], v[110:113], v[106:109], v[82:85]
	ds_read2_b64 v[110:113], v3 offset0:40 offset1:44
	v_add_u32_e32 v3, 0xe000, v185
	s_waitcnt lgkmcnt(0)
	v_mfma_f32_16x16x32_bf16 v[82:85], v[110:113], v[102:105], v[82:85]
	ds_read2_b64 v[110:113], v3 offset0:64 offset1:68
	s_waitcnt lgkmcnt(0)
	v_mfma_f32_16x16x32_bf16 v[74:77], v[110:113], v[106:109], v[74:77]
	ds_read2_b64 v[110:113], v3 offset0:72 offset1:76
	v_add_u32_e32 v3, 0xe800, v185
	s_waitcnt lgkmcnt(0)
	v_mfma_f32_16x16x32_bf16 v[74:77], v[110:113], v[102:105], v[74:77]
	ds_read2_b64 v[110:113], v3 offset0:96 offset1:100
	s_waitcnt lgkmcnt(0)
	v_mfma_f32_16x16x32_bf16 v[86:89], v[110:113], v[106:109], v[86:89]
	ds_read2_b64 v[106:109], v3 offset0:104 offset1:108
	s_waitcnt lgkmcnt(0)
	s_barrier
	s_waitcnt lgkmcnt(0)
	v_mfma_f32_16x16x32_bf16 v[86:89], v[106:109], v[102:105], v[86:89]
	s_cbranch_vccnz .LBB0_957
	s_waitcnt vmcnt(25)
	ds_write_b128 v170, v[6:9]
	ds_write_b128 v170, v[14:17] offset:17408
	s_waitcnt vmcnt(24)
	ds_write_b128 v171, v[18:21] offset:44032
	s_waitcnt vmcnt(23)
	ds_write_b128 v173, v[22:25]
	ds_write_b128 v173, v[10:13] offset:17408
	s_waitcnt vmcnt(22)
	ds_write_b128 v174, v[26:29] offset:44032
	s_waitcnt vmcnt(21)
	ds_write_b128 v175, v[30:33]
	ds_write_b128 v175, v[34:37] offset:17408
	s_waitcnt vmcnt(20)
	ds_write_b128 v176, v[38:41] offset:44032
	s_waitcnt vmcnt(19)
	ds_write_b128 v177, v[42:45]
	ds_write_b128 v177, v[46:49] offset:17408
	s_waitcnt vmcnt(18)
	ds_write_b128 v178, v[54:57] offset:44032
	s_waitcnt vmcnt(17)
	ds_write_b128 v171, v[58:61] offset:34816
	ds_write_b128 v171, v[62:65] offset:62464
	s_waitcnt vmcnt(16)
	ds_write_b128 v174, v[66:69] offset:34816
	ds_write_b128 v174, v[70:73] offset:62464
	s_branch .LBB0_957
